# inproj k-loop: 3-stage LDS ring, LDS-DMA for even k-steps paired with register-staged odd k-steps, loads spread among MFMAs
# speedup vs baseline: 1.0240x; 1.0179x over previous
; DI int otid() { int t; asm volatile("v_mov_b32 %0, %1" : "=v"(t) : "v"((int)threadIdx.x)); __builtin_assume(t >= 0 && t < 256); return t; }
; #define BLOADG(kt) do { \
;     _Pragma("unroll") for (int i = 0; i < 2; ++i) ra[i] = *(const u32x4*)(ap + (size_t)(64 * i) * lda + (kt) * 32); \
;     _Pragma("unroll") for (int i = 0; i < 4; ++i) rb[i] = *(const u32x4*)(bp + (size_t)((i & 1) * s1 + (i >> 1) * s2) * ldb + (kt) * 32); } while (0)
; #define BSTOREG(st) do { \
;     _Pragma("unroll") for (int i = 0; i < 2; ++i) *(u32x4*)(sA + (st) * BGA + so + 64 * i * 32) = ra[i]; \
;     _Pragma("unroll") for (int i = 0; i < 4; ++i) *(u32x4*)(sB + (st) * BGB + so + 64 * i * 32) = rb[i]; } while (0)
;   bf16_t* sA = (bf16_t*)smem; bf16_t* sB = sA + 2 * BGA;
;   const int tid = otid(), lane = tid & 63, wid = tid >> 6;
;   const int wm = wid >> 1, wn = wid & 1, fr = lane & 15, fq = lane >> 4;
;   const int nk = K >> 5;
;   const bf16_t* ap = A + (size_t)(tid >> 2) * lda + (tid & 3) * 8;
;   const bf16_t* bp = Bt + (size_t)(brow >= 0 ? brow : (tid >> 2)) * ldb + (tid & 3) * 8;
;   const int so = (tid >> 2) * 32 + (((tid & 3) ^ (((tid >> 5) & 1) << 1)) * 8);
;   const int fo = fr * 32 + ((fq ^ (((fr >> 3) & 1) << 1)) * 8);
;   u32x4 ra[2], rb[4];
;     ...
;   __syncthreads();
;   BLOADG(0); BSTOREG(0);
;   if (nk > 1) BLOADG(1);
;   __syncthreads();
; DI void inproj_tile(const Params& p, int l, int tile, char* smem) {
;   const int mt = tile & 255, nt = tile >> 8;
;   f32x4 acc[4][8]; zero_acc8(acc);
.LBB0_248:
	s_lshl_b32 s0, s13, 8
	s_add_i32 s11, s0, s12
	s_lshl_b32 s0, s12, 7
	s_and_b32 s12, s0, 0x7f80
	s_lshl_b32 s94, s12, 11
	s_add_u32 s0, s31, s94
	s_addc_u32 s1, s30, 0
	s_and_b32 s11, s11, 0xffffff00
	s_ashr_i32 s13, s11, 31
	s_add_u32 s22, s6, s11
	s_addc_u32 s23, 0, s13
	v_mov_b32 v4, v188
	s_lshl_b64 s[22:23], s[22:23], 11
	v_lshrrev_b32_e32 v15, 2, v4
	v_lshlrev_b32_e32 v0, 11, v15
	v_and_b32_e32 v52, 3, v4
	s_add_u32 s22, s58, s22
	v_lshl_add_u64 v[2:3], s[0:1], 0, v[0:1]
	v_lshlrev_b32_e32 v40, 4, v52
	v_mov_b32_e32 v41, v1
	s_addc_u32 s23, s59, s23
	v_lshl_add_u64 v[42:43], v[2:3], 0, v[40:41]
	v_lshl_add_u64 v[2:3], s[22:23], 0, v[0:1]
	v_add_co_u32_e32 v44, vcc, s77, v42
	v_lshl_add_u64 v[154:155], v[2:3], 0, v[40:41]
	s_nop 0
	v_addc_co_u32_e32 v45, vcc, 0, v43, vcc
	v_add_co_u32_e32 v46, vcc, s77, v154
	s_nop 1
	v_addc_co_u32_e32 v47, vcc, 0, v155, vcc
	v_add_co_u32_e32 v48, vcc, s92, v154
	s_barrier
	s_nop 0
	v_addc_co_u32_e32 v49, vcc, 0, v155, vcc
	v_add_co_u32_e32 v50, vcc, s81, v154
	s_nop 1
	v_addc_co_u32_e32 v51, vcc, 0, v155, vcc
	s_mov_b32 s24, s22
	s_mov_b32 s25, s23
	v_lshrrev_b32_e32 v157, 6, v188
	v_lshrrev_b32_e32 v155, 4, v188
	v_lshlrev_b32_e32 v157, 10, v157
	v_and_b32_e32 v155, 2, v155
	v_and_b32_e32 v156, 3, v188
	v_readfirstlane_b32 s22, v157
	v_lshrrev_b32_e32 v154, 2, v188
	v_xor_b32_e32 v155, v155, v156
	v_lshlrev_b32_e32 v154, 11, v154
	v_lshl_or_b32 v154, v155, 4, v154
	v_add_u32_e32 v155, 0x20000, v154
	v_add_u32_e32 v156, 0x40000, v154
	v_add_u32_e32 v157, 0x60000, v154
	s_nop 1
	s_mov_b32 m0, s22
	s_nop 0
	global_load_lds_dwordx4 v154, s[0:1]
	s_add_u32 m0, s22, 0x1fc0
	s_nop 0
	global_load_lds_dwordx4 v154, s[0:1] offset:64
	s_add_u32 m0, s22, 0x1000
	s_nop 0
	global_load_lds_dwordx4 v155, s[0:1]
	s_add_u32 m0, s22, 0x2fc0
	s_nop 0
	global_load_lds_dwordx4 v155, s[0:1] offset:64
	s_add_u32 m0, s22, 0x4000
	s_nop 0
	global_load_lds_dwordx4 v154, s[24:25]
	s_add_u32 m0, s22, 0x7fc0
	s_nop 0
	global_load_lds_dwordx4 v154, s[24:25] offset:64
	s_add_u32 m0, s22, 0x5000
	s_nop 0
	global_load_lds_dwordx4 v155, s[24:25]
	s_add_u32 m0, s22, 0x8fc0
	s_nop 0
	global_load_lds_dwordx4 v155, s[24:25] offset:64
	s_add_u32 m0, s22, 0x6000
	s_nop 0
	global_load_lds_dwordx4 v156, s[24:25]
	s_add_u32 m0, s22, 0x9fc0
	s_nop 0
	global_load_lds_dwordx4 v156, s[24:25] offset:64
	s_add_u32 m0, s22, 0x7000
	s_nop 0
	global_load_lds_dwordx4 v157, s[24:25]
	s_add_u32 m0, s22, 0xafc0
	s_nop 0
	global_load_lds_dwordx4 v157, s[24:25] offset:64
	s_add_u32 s0, s0, 0x80
	s_addc_u32 s1, s1, 0
	s_add_u32 s24, s24, 0x80
	s_addc_u32 s25, s25, 0
	v_lshrrev_b32_e32 v41, 4, v4
	v_lshlrev_b32_e32 v53, 6, v4
	v_bitop3_b32 v52, v41, v52, 2 bitop3:0x6c
	v_and_b32_e32 v56, 2, v15
	v_lshlrev_b32_e32 v15, 6, v15
	v_and_b32_e32 v57, 0x3c0, v53
	v_bitop3_b32 v41, v41, v56, 3 bitop3:0x6c
	v_lshl_or_b32 v159, v52, 4, v15
	v_lshl_add_u64 v[52:53], s[94:95], 0, v[0:1]
	v_mov_b32_e32 v2, 0
	v_lshlrev_b32_e32 v54, 5, v4
	v_lshlrev_b32_e32 v55, 7, v4
	v_lshl_or_b32 v0, v41, 4, v57
	v_or_b32_e32 v52, v52, v40
	s_mov_b32 s13, 0
	v_mov_b32_e32 v3, v2
	v_mov_b32_e32 v4, v2
	v_mov_b32_e32 v5, v2
	v_mov_b32_e32 v6, v2
	v_mov_b32_e32 v7, v2
	v_mov_b32_e32 v8, v2
	v_mov_b32_e32 v9, v2
	v_mov_b32_e32 v10, v2
	v_mov_b32_e32 v11, v2
	v_mov_b32_e32 v12, v2
	v_mov_b32_e32 v13, v2
	v_mov_b32_e32 v14, v2
	v_and_or_b32 v158, v54, s85, v0
	v_and_or_b32 v0, v55, s26, v0
	v_mov_b32_e32 v15, v2
	v_mov_b32_e32 v40, v2
	v_mov_b32_e32 v41, v2
	v_mov_b32_e32 v46, v2
	v_mov_b32_e32 v47, v2
	v_mov_b32_e32 v48, v2
	v_mov_b32_e32 v49, v2
	v_mov_b32_e32 v54, v2
	v_mov_b32_e32 v55, v2
	v_mov_b32_e32 v56, v2
	v_mov_b32_e32 v57, v2
	v_mov_b32_e32 v62, v2
	v_mov_b32_e32 v63, v2
	v_mov_b32_e32 v64, v2
	v_mov_b32_e32 v65, v2
	v_mov_b32_e32 v16, v2
	v_mov_b32_e32 v17, v2
	v_mov_b32_e32 v38, v2
	v_mov_b32_e32 v39, v2
	v_mov_b32_e32 v18, v2
	v_mov_b32_e32 v19, v2
	v_mov_b32_e32 v20, v2
	v_mov_b32_e32 v21, v2
	v_mov_b32_e32 v22, v2
	v_mov_b32_e32 v23, v2
	v_mov_b32_e32 v24, v2
	v_mov_b32_e32 v25, v2
	v_mov_b32_e32 v26, v2
	v_mov_b32_e32 v27, v2
	v_mov_b32_e32 v28, v2
	v_mov_b32_e32 v29, v2
	v_mov_b32_e32 v30, v2
	v_mov_b32_e32 v31, v2
	v_mov_b32_e32 v32, v2
	v_mov_b32_e32 v33, v2
	v_mov_b32_e32 v70, v2
	v_mov_b32_e32 v71, v2
	v_mov_b32_e32 v72, v2
	v_mov_b32_e32 v73, v2
	v_mov_b32_e32 v78, v2
	v_mov_b32_e32 v79, v2
	v_mov_b32_e32 v80, v2
	v_mov_b32_e32 v81, v2
	v_mov_b32_e32 v86, v2
	v_mov_b32_e32 v87, v2
	v_mov_b32_e32 v88, v2
	v_mov_b32_e32 v89, v2
	v_mov_b32_e32 v94, v2
	v_mov_b32_e32 v95, v2
	v_mov_b32_e32 v96, v2
	v_mov_b32_e32 v97, v2
	v_mov_b32_e32 v34, v2
	v_mov_b32_e32 v35, v2
	v_mov_b32_e32 v36, v2
	v_mov_b32_e32 v37, v2
	v_mov_b32_e32 v42, v2
	v_mov_b32_e32 v43, v2
	v_mov_b32_e32 v44, v2
	v_mov_b32_e32 v45, v2
	v_mov_b32_e32 v50, v2
	v_mov_b32_e32 v51, v2
	v_mov_b32_e32 v52, v2
	v_mov_b32_e32 v53, v2
	v_mov_b32_e32 v58, v2
	v_mov_b32_e32 v59, v2
	v_mov_b32_e32 v60, v2
	v_mov_b32_e32 v61, v2
	v_mov_b32_e32 v98, v2
	v_mov_b32_e32 v99, v2
	v_mov_b32_e32 v100, v2
	v_mov_b32_e32 v101, v2
	v_mov_b32_e32 v102, v2
	v_mov_b32_e32 v103, v2
	v_mov_b32_e32 v104, v2
	v_mov_b32_e32 v105, v2
	v_mov_b32_e32 v106, v2
	v_mov_b32_e32 v107, v2
	v_mov_b32_e32 v108, v2
	v_mov_b32_e32 v109, v2
	v_mov_b32_e32 v110, v2
	v_mov_b32_e32 v111, v2
	v_mov_b32_e32 v112, v2
	v_mov_b32_e32 v113, v2
	v_mov_b32_e32 v66, v2
	v_mov_b32_e32 v67, v2
	v_mov_b32_e32 v68, v2
	v_mov_b32_e32 v69, v2
	v_mov_b32_e32 v74, v2
	v_mov_b32_e32 v75, v2
	v_mov_b32_e32 v76, v2
	v_mov_b32_e32 v77, v2
	v_mov_b32_e32 v82, v2
	v_mov_b32_e32 v83, v2
	v_mov_b32_e32 v84, v2
	v_mov_b32_e32 v85, v2
	v_mov_b32_e32 v90, v2
	v_mov_b32_e32 v91, v2
	v_mov_b32_e32 v92, v2
	v_mov_b32_e32 v93, v2
	v_mov_b32_e32 v114, v2
	v_mov_b32_e32 v115, v2
	v_mov_b32_e32 v116, v2
	v_mov_b32_e32 v117, v2
	v_mov_b32_e32 v118, v2
	v_mov_b32_e32 v119, v2
	v_mov_b32_e32 v120, v2
	v_mov_b32_e32 v121, v2
	v_mov_b32_e32 v146, v2
	v_mov_b32_e32 v147, v2
	v_mov_b32_e32 v148, v2
	v_mov_b32_e32 v149, v2
	v_mov_b32_e32 v150, v2
	v_mov_b32_e32 v151, v2
	v_mov_b32_e32 v152, v2
	v_mov_b32_e32 v153, v2
	v_add_u32_e32 v226, 0x8000, v158
	v_lshlrev_b32_e32 v228, 4, v188
	v_add_u32_e32 v227, 0x8000, v228
	v_lshlrev_b32_e32 v212, 11, v188
	v_and_b32_e32 v213, 0x3ffff, v212
	s_waitcnt vmcnt(0)
	s_barrier
; #define BLOADG(kt) do { \
;     _Pragma("unroll") for (int i = 0; i < 2; ++i) ra[i] = *(const u32x4*)(ap + (size_t)(64 * i) * lda + (kt) * 32); \
;     _Pragma("unroll") for (int i = 0; i < 4; ++i) rb[i] = *(const u32x4*)(bp + (size_t)((i & 1) * s1 + (i >> 1) * s2) * ldb + (kt) * 32); } while (0)
; #define BSTOREG(st) do { \
;     _Pragma("unroll") for (int i = 0; i < 2; ++i) *(u32x4*)(sA + (st) * BGA + so + 64 * i * 32) = ra[i]; \
;     _Pragma("unroll") for (int i = 0; i < 4; ++i) *(u32x4*)(sB + (st) * BGB + so + 64 * i * 32) = rb[i]; } while (0)
;     ...
;   for (int kt = 0; kt < nk; ++kt) {
;     const int cur = kt & 1;
;     if (kt + 1 < nk) { BSTOREG(cur ^ 1); if (kt + 2 < nk) BLOADG(kt + 2); }
;     const bf16_t* cA = sA + cur * BGA + (wm * 64) * 32 + fo; const bf16_t* cB = sB + cur * BGB + (wn * 128) * 32 + fo;
;     bf16x8 af[4];
; #pragma unroll
;     for (int mi = 0; mi < 4; ++mi) af[mi] = *(const bf16x8*)(cA + mi * 16 * 32);
; #pragma unroll
;     for (int nh = 0; nh < 2; ++nh) {
;       bf16x8 bfr[4];
; #pragma unroll
;       for (int ni = 0; ni < 4; ++ni) bfr[ni] = *(const bf16x8*)(cB + (nh * 4 + ni) * 16 * 32);
; #pragma unroll
;       for (int mi = 0; mi < 4; ++mi)
; #pragma unroll
;         for (int ni = 0; ni < 4; ++ni) acc[mi][nh * 4 + ni] = __builtin_amdgcn_mfma_f32_16x16x32_bf16(bfr[ni], af[mi], acc[mi][nh * 4 + ni], 0, 0, 0);
;     }
;     __syncthreads();
.LBB0_249:
	ds_read_b128 v[160:163], v158 offset:0
	ds_read_b128 v[164:167], v158 offset:1024
	ds_read_b128 v[168:171], v158 offset:2048
	ds_read_b128 v[172:175], v158 offset:3072
	ds_read_b128 v[176:179], v0 offset:16384
	ds_read_b128 v[180:183], v0 offset:17408
	ds_read_b128 v[184:187], v0 offset:18432
	ds_read_b128 v[206:209], v0 offset:19456
	s_waitcnt lgkmcnt(7)
	s_waitcnt lgkmcnt(3)
	v_mfma_f32_16x16x32_bf16 v[150:153], v[176:179], v[160:163], v[150:153]
	v_mfma_f32_16x16x32_bf16 v[110:113], v[176:179], v[164:167], v[110:113]
	v_mfma_f32_16x16x32_bf16 v[94:97], v[176:179], v[168:171], v[94:97]
	v_mfma_f32_16x16x32_bf16 v[62:65], v[176:179], v[172:175], v[62:65]
	ds_read_b128 v[176:179], v0 offset:20480
	s_add_u32 m0, s22, 0x10400
	s_nop 0
	global_load_lds_dwordx4 v154, s[0:1]
	global_load_dwordx4 v[126:129], v154, s[0:1] offset:64
	s_waitcnt lgkmcnt(3)
	v_mfma_f32_16x16x32_bf16 v[146:149], v[180:183], v[160:163], v[146:149]
	v_mfma_f32_16x16x32_bf16 v[106:109], v[180:183], v[164:167], v[106:109]
	v_mfma_f32_16x16x32_bf16 v[86:89], v[180:183], v[168:171], v[86:89]
	v_mfma_f32_16x16x32_bf16 v[54:57], v[180:183], v[172:175], v[54:57]
	ds_read_b128 v[180:183], v0 offset:21504
	s_add_u32 m0, s22, 0x11400
	s_nop 0
	global_load_lds_dwordx4 v155, s[0:1]
	global_load_dwordx4 v[122:125], v155, s[0:1] offset:64
	s_waitcnt lgkmcnt(3)
	v_mfma_f32_16x16x32_bf16 v[118:121], v[184:187], v[160:163], v[118:121]
	v_mfma_f32_16x16x32_bf16 v[102:105], v[184:187], v[164:167], v[102:105]
	v_mfma_f32_16x16x32_bf16 v[78:81], v[184:187], v[168:171], v[78:81]
	v_mfma_f32_16x16x32_bf16 v[46:49], v[184:187], v[172:175], v[46:49]
	ds_read_b128 v[184:187], v0 offset:22528
	s_add_u32 m0, s22, 0xc000
	s_nop 0
	global_load_lds_dwordx4 v154, s[24:25]
	global_load_dwordx4 v[138:141], v154, s[24:25] offset:64
	s_waitcnt lgkmcnt(3)
	v_mfma_f32_16x16x32_bf16 v[114:117], v[206:209], v[160:163], v[114:117]
	v_mfma_f32_16x16x32_bf16 v[98:101], v[206:209], v[164:167], v[98:101]
	v_mfma_f32_16x16x32_bf16 v[70:73], v[206:209], v[168:171], v[70:73]
	v_mfma_f32_16x16x32_bf16 v[38:41], v[206:209], v[172:175], v[38:41]
	ds_read_b128 v[206:209], v0 offset:23552
	s_add_u32 m0, s22, 0xd000
	s_nop 0
	global_load_lds_dwordx4 v155, s[24:25]
	global_load_dwordx4 v[134:137], v155, s[24:25] offset:64
	s_waitcnt lgkmcnt(3)
	v_mfma_f32_16x16x32_bf16 v[90:93], v[176:179], v[160:163], v[90:93]
	v_mfma_f32_16x16x32_bf16 v[58:61], v[176:179], v[164:167], v[58:61]
	v_mfma_f32_16x16x32_bf16 v[30:33], v[176:179], v[168:171], v[30:33]
	v_mfma_f32_16x16x32_bf16 v[14:17], v[176:179], v[172:175], v[14:17]
	s_add_u32 m0, s22, 0xe000
	s_nop 0
	global_load_lds_dwordx4 v156, s[24:25]
	global_load_dwordx4 v[130:133], v156, s[24:25] offset:64
	s_waitcnt lgkmcnt(2)
	v_mfma_f32_16x16x32_bf16 v[82:85], v[180:183], v[160:163], v[82:85]
	v_mfma_f32_16x16x32_bf16 v[50:53], v[180:183], v[164:167], v[50:53]
	v_mfma_f32_16x16x32_bf16 v[26:29], v[180:183], v[168:171], v[26:29]
	v_mfma_f32_16x16x32_bf16 v[10:13], v[180:183], v[172:175], v[10:13]
	s_add_u32 m0, s22, 0xf000
	s_nop 0
	global_load_lds_dwordx4 v157, s[24:25]
	global_load_dwordx4 v[142:145], v157, s[24:25] offset:64
	s_add_u32 s0, s0, 0x80
	s_addc_u32 s1, s1, 0
	s_add_u32 s24, s24, 0x80
	s_addc_u32 s25, s25, 0
	s_waitcnt lgkmcnt(1)
	v_mfma_f32_16x16x32_bf16 v[74:77], v[184:187], v[160:163], v[74:77]
	v_mfma_f32_16x16x32_bf16 v[42:45], v[184:187], v[164:167], v[42:45]
	v_mfma_f32_16x16x32_bf16 v[22:25], v[184:187], v[168:171], v[22:25]
	v_mfma_f32_16x16x32_bf16 v[6:9], v[184:187], v[172:175], v[6:9]
	s_waitcnt lgkmcnt(0)
	s_barrier
	v_mfma_f32_16x16x32_bf16 v[66:69], v[206:209], v[160:163], v[66:69]
	v_mfma_f32_16x16x32_bf16 v[34:37], v[206:209], v[164:167], v[34:37]
	v_mfma_f32_16x16x32_bf16 v[18:21], v[206:209], v[168:171], v[18:21]
	v_mfma_f32_16x16x32_bf16 v[2:5], v[206:209], v[172:175], v[2:5]
	ds_read_b128 v[160:163], v158 offset:8192
	ds_read_b128 v[164:167], v158 offset:9216
	ds_read_b128 v[168:171], v158 offset:10240
	ds_read_b128 v[172:175], v158 offset:11264
	ds_read_b128 v[176:179], v0 offset:32768
	ds_read_b128 v[180:183], v0 offset:33792
	ds_read_b128 v[184:187], v0 offset:34816
	ds_read_b128 v[206:209], v0 offset:35840
	s_waitcnt lgkmcnt(7)
	s_waitcnt lgkmcnt(3)
	v_mfma_f32_16x16x32_bf16 v[150:153], v[176:179], v[160:163], v[150:153]
	v_mfma_f32_16x16x32_bf16 v[110:113], v[176:179], v[164:167], v[110:113]
	v_mfma_f32_16x16x32_bf16 v[94:97], v[176:179], v[168:171], v[94:97]
	v_mfma_f32_16x16x32_bf16 v[62:65], v[176:179], v[172:175], v[62:65]
	ds_read_b128 v[176:179], v0 offset:36864
	s_waitcnt lgkmcnt(3)
	v_mfma_f32_16x16x32_bf16 v[146:149], v[180:183], v[160:163], v[146:149]
	v_mfma_f32_16x16x32_bf16 v[106:109], v[180:183], v[164:167], v[106:109]
	v_mfma_f32_16x16x32_bf16 v[86:89], v[180:183], v[168:171], v[86:89]
	v_mfma_f32_16x16x32_bf16 v[54:57], v[180:183], v[172:175], v[54:57]
	ds_read_b128 v[180:183], v0 offset:37888
	s_waitcnt lgkmcnt(3)
	v_mfma_f32_16x16x32_bf16 v[118:121], v[184:187], v[160:163], v[118:121]
	v_mfma_f32_16x16x32_bf16 v[102:105], v[184:187], v[164:167], v[102:105]
	v_mfma_f32_16x16x32_bf16 v[78:81], v[184:187], v[168:171], v[78:81]
	v_mfma_f32_16x16x32_bf16 v[46:49], v[184:187], v[172:175], v[46:49]
	ds_read_b128 v[184:187], v0 offset:38912
	s_waitcnt lgkmcnt(3)
	v_mfma_f32_16x16x32_bf16 v[114:117], v[206:209], v[160:163], v[114:117]
	v_mfma_f32_16x16x32_bf16 v[98:101], v[206:209], v[164:167], v[98:101]
	v_mfma_f32_16x16x32_bf16 v[70:73], v[206:209], v[168:171], v[70:73]
	v_mfma_f32_16x16x32_bf16 v[38:41], v[206:209], v[172:175], v[38:41]
	ds_read_b128 v[206:209], v0 offset:39936
	s_waitcnt lgkmcnt(3)
	v_mfma_f32_16x16x32_bf16 v[90:93], v[176:179], v[160:163], v[90:93]
	v_mfma_f32_16x16x32_bf16 v[58:61], v[176:179], v[164:167], v[58:61]
	v_mfma_f32_16x16x32_bf16 v[30:33], v[176:179], v[168:171], v[30:33]
	v_mfma_f32_16x16x32_bf16 v[14:17], v[176:179], v[172:175], v[14:17]
	s_waitcnt vmcnt(0)
	s_waitcnt lgkmcnt(2)
	v_mfma_f32_16x16x32_bf16 v[82:85], v[180:183], v[160:163], v[82:85]
	ds_write_b128 v228, v[126:129] offset:0
	v_mfma_f32_16x16x32_bf16 v[50:53], v[180:183], v[164:167], v[50:53]
	ds_write_b128 v228, v[122:125] offset:4096
	v_mfma_f32_16x16x32_bf16 v[26:29], v[180:183], v[168:171], v[26:29]
	ds_write_b128 v228, v[138:141] offset:16384
	v_mfma_f32_16x16x32_bf16 v[10:13], v[180:183], v[172:175], v[10:13]
	ds_write_b128 v228, v[134:137] offset:20480
	s_waitcnt lgkmcnt(5)
	v_mfma_f32_16x16x32_bf16 v[74:77], v[184:187], v[160:163], v[74:77]
	ds_write_b128 v228, v[130:133] offset:24576
	v_mfma_f32_16x16x32_bf16 v[42:45], v[184:187], v[164:167], v[42:45]
	ds_write_b128 v228, v[142:145] offset:28672
	v_mfma_f32_16x16x32_bf16 v[22:25], v[184:187], v[168:171], v[22:25]
	v_mfma_f32_16x16x32_bf16 v[6:9], v[184:187], v[172:175], v[6:9]
	s_waitcnt lgkmcnt(0)
	s_barrier
; #define BLOADG(kt) do { \
;     _Pragma("unroll") for (int i = 0; i < 2; ++i) ra[i] = *(const u32x4*)(ap + (size_t)(64 * i) * lda + (kt) * 32); \
;     _Pragma("unroll") for (int i = 0; i < 4; ++i) rb[i] = *(const u32x4*)(bp + (size_t)((i & 1) * s1 + (i >> 1) * s2) * ldb + (kt) * 32); } while (0)
; #define BSTOREG(st) do { \
;     _Pragma("unroll") for (int i = 0; i < 2; ++i) *(u32x4*)(sA + (st) * BGA + so + 64 * i * 32) = ra[i]; \
;     _Pragma("unroll") for (int i = 0; i < 4; ++i) *(u32x4*)(sB + (st) * BGB + so + 64 * i * 32) = rb[i]; } while (0)
;     ...
;   for (int kt = 0; kt < nk; ++kt) {
;     const int cur = kt & 1;
;     if (kt + 1 < nk) { BSTOREG(cur ^ 1); if (kt + 2 < nk) BLOADG(kt + 2); }
;     const bf16_t* cA = sA + cur * BGA + (wm * 64) * 32 + fo; const bf16_t* cB = sB + cur * BGB + (wn * 128) * 32 + fo;
;     bf16x8 af[4];
; #pragma unroll
;     for (int mi = 0; mi < 4; ++mi) af[mi] = *(const bf16x8*)(cA + mi * 16 * 32);
; #pragma unroll
;     for (int nh = 0; nh < 2; ++nh) {
;       bf16x8 bfr[4];
; #pragma unroll
;       for (int ni = 0; ni < 4; ++ni) bfr[ni] = *(const bf16x8*)(cB + (nh * 4 + ni) * 16 * 32);
; #pragma unroll
;       for (int mi = 0; mi < 4; ++mi)
; #pragma unroll
;         for (int ni = 0; ni < 4; ++ni) acc[mi][nh * 4 + ni] = __builtin_amdgcn_mfma_f32_16x16x32_bf16(bfr[ni], af[mi], acc[mi][nh * 4 + ni], 0, 0, 0);
;     }
;     __syncthreads();
	v_mfma_f32_16x16x32_bf16 v[66:69], v[206:209], v[160:163], v[66:69]
	v_mfma_f32_16x16x32_bf16 v[34:37], v[206:209], v[164:167], v[34:37]
	v_mfma_f32_16x16x32_bf16 v[18:21], v[206:209], v[168:171], v[18:21]
	v_mfma_f32_16x16x32_bf16 v[2:5], v[206:209], v[172:175], v[2:5]
	ds_read_b128 v[160:163], v226 offset:33792
	ds_read_b128 v[164:167], v226 offset:34816
	ds_read_b128 v[168:171], v226 offset:35840
	ds_read_b128 v[172:175], v226 offset:36864
	ds_read_b128 v[176:179], v0 offset:49152
	ds_read_b128 v[180:183], v0 offset:50176
	ds_read_b128 v[184:187], v0 offset:51200
	ds_read_b128 v[206:209], v0 offset:52224
	s_waitcnt lgkmcnt(7)
	s_waitcnt lgkmcnt(3)
	v_mfma_f32_16x16x32_bf16 v[150:153], v[176:179], v[160:163], v[150:153]
	v_mfma_f32_16x16x32_bf16 v[110:113], v[176:179], v[164:167], v[110:113]
	v_mfma_f32_16x16x32_bf16 v[94:97], v[176:179], v[168:171], v[94:97]
	v_mfma_f32_16x16x32_bf16 v[62:65], v[176:179], v[172:175], v[62:65]
	ds_read_b128 v[176:179], v0 offset:53248
	s_add_u32 m0, s22, 0x2000
	s_nop 0
	global_load_lds_dwordx4 v154, s[0:1]
	global_load_dwordx4 v[126:129], v154, s[0:1] offset:64
	s_waitcnt lgkmcnt(3)
	v_mfma_f32_16x16x32_bf16 v[146:149], v[180:183], v[160:163], v[146:149]
	v_mfma_f32_16x16x32_bf16 v[106:109], v[180:183], v[164:167], v[106:109]
	v_mfma_f32_16x16x32_bf16 v[86:89], v[180:183], v[168:171], v[86:89]
	v_mfma_f32_16x16x32_bf16 v[54:57], v[180:183], v[172:175], v[54:57]
	ds_read_b128 v[180:183], v0 offset:54272
	s_add_u32 m0, s22, 0x3000
	s_nop 0
	global_load_lds_dwordx4 v155, s[0:1]
	global_load_dwordx4 v[122:125], v155, s[0:1] offset:64
	s_waitcnt lgkmcnt(3)
	v_mfma_f32_16x16x32_bf16 v[118:121], v[184:187], v[160:163], v[118:121]
	v_mfma_f32_16x16x32_bf16 v[102:105], v[184:187], v[164:167], v[102:105]
	v_mfma_f32_16x16x32_bf16 v[78:81], v[184:187], v[168:171], v[78:81]
	v_mfma_f32_16x16x32_bf16 v[46:49], v[184:187], v[172:175], v[46:49]
	ds_read_b128 v[184:187], v0 offset:55296
	s_add_u32 m0, s22, 0x8000
	s_nop 0
	global_load_lds_dwordx4 v154, s[24:25]
	global_load_dwordx4 v[138:141], v154, s[24:25] offset:64
	s_waitcnt lgkmcnt(3)
	v_mfma_f32_16x16x32_bf16 v[114:117], v[206:209], v[160:163], v[114:117]
	v_mfma_f32_16x16x32_bf16 v[98:101], v[206:209], v[164:167], v[98:101]
	v_mfma_f32_16x16x32_bf16 v[70:73], v[206:209], v[168:171], v[70:73]
	v_mfma_f32_16x16x32_bf16 v[38:41], v[206:209], v[172:175], v[38:41]
	ds_read_b128 v[206:209], v0 offset:56320
	s_add_u32 m0, s22, 0x9000
	s_nop 0
	global_load_lds_dwordx4 v155, s[24:25]
	global_load_dwordx4 v[134:137], v155, s[24:25] offset:64
	s_waitcnt lgkmcnt(3)
	v_mfma_f32_16x16x32_bf16 v[90:93], v[176:179], v[160:163], v[90:93]
	v_mfma_f32_16x16x32_bf16 v[58:61], v[176:179], v[164:167], v[58:61]
	v_mfma_f32_16x16x32_bf16 v[30:33], v[176:179], v[168:171], v[30:33]
	v_mfma_f32_16x16x32_bf16 v[14:17], v[176:179], v[172:175], v[14:17]
	s_add_u32 m0, s22, 0xa000
	s_nop 0
	global_load_lds_dwordx4 v156, s[24:25]
	global_load_dwordx4 v[130:133], v156, s[24:25] offset:64
	s_waitcnt lgkmcnt(2)
	v_mfma_f32_16x16x32_bf16 v[82:85], v[180:183], v[160:163], v[82:85]
	v_mfma_f32_16x16x32_bf16 v[50:53], v[180:183], v[164:167], v[50:53]
	v_mfma_f32_16x16x32_bf16 v[26:29], v[180:183], v[168:171], v[26:29]
	v_mfma_f32_16x16x32_bf16 v[10:13], v[180:183], v[172:175], v[10:13]
	s_add_u32 m0, s22, 0xb000
	s_nop 0
	global_load_lds_dwordx4 v157, s[24:25]
	global_load_dwordx4 v[142:145], v157, s[24:25] offset:64
	s_add_u32 s0, s0, 0x80
	s_addc_u32 s1, s1, 0
	s_add_u32 s24, s24, 0x80
	s_addc_u32 s25, s25, 0
	s_waitcnt lgkmcnt(1)
	v_mfma_f32_16x16x32_bf16 v[74:77], v[184:187], v[160:163], v[74:77]
	v_mfma_f32_16x16x32_bf16 v[42:45], v[184:187], v[164:167], v[42:45]
	v_mfma_f32_16x16x32_bf16 v[22:25], v[184:187], v[168:171], v[22:25]
	v_mfma_f32_16x16x32_bf16 v[6:9], v[184:187], v[172:175], v[6:9]
	s_waitcnt lgkmcnt(0)
	s_barrier
	v_mfma_f32_16x16x32_bf16 v[66:69], v[206:209], v[160:163], v[66:69]
	v_mfma_f32_16x16x32_bf16 v[34:37], v[206:209], v[164:167], v[34:37]
	v_mfma_f32_16x16x32_bf16 v[18:21], v[206:209], v[168:171], v[18:21]
	v_mfma_f32_16x16x32_bf16 v[2:5], v[206:209], v[172:175], v[2:5]
	ds_read_b128 v[160:163], v158 offset:0
	ds_read_b128 v[164:167], v158 offset:1024
	ds_read_b128 v[168:171], v158 offset:2048
	ds_read_b128 v[172:175], v158 offset:3072
	ds_read_b128 v[176:179], v0 offset:16384
	ds_read_b128 v[180:183], v0 offset:17408
	ds_read_b128 v[184:187], v0 offset:18432
	ds_read_b128 v[206:209], v0 offset:19456
	s_waitcnt lgkmcnt(7)
	s_waitcnt lgkmcnt(3)
	v_mfma_f32_16x16x32_bf16 v[150:153], v[176:179], v[160:163], v[150:153]
	v_mfma_f32_16x16x32_bf16 v[110:113], v[176:179], v[164:167], v[110:113]
	v_mfma_f32_16x16x32_bf16 v[94:97], v[176:179], v[168:171], v[94:97]
	v_mfma_f32_16x16x32_bf16 v[62:65], v[176:179], v[172:175], v[62:65]
	ds_read_b128 v[176:179], v0 offset:20480
	s_waitcnt lgkmcnt(3)
	v_mfma_f32_16x16x32_bf16 v[146:149], v[180:183], v[160:163], v[146:149]
	v_mfma_f32_16x16x32_bf16 v[106:109], v[180:183], v[164:167], v[106:109]
	v_mfma_f32_16x16x32_bf16 v[86:89], v[180:183], v[168:171], v[86:89]
	v_mfma_f32_16x16x32_bf16 v[54:57], v[180:183], v[172:175], v[54:57]
	ds_read_b128 v[180:183], v0 offset:21504
	s_waitcnt lgkmcnt(3)
	v_mfma_f32_16x16x32_bf16 v[118:121], v[184:187], v[160:163], v[118:121]
	v_mfma_f32_16x16x32_bf16 v[102:105], v[184:187], v[164:167], v[102:105]
	v_mfma_f32_16x16x32_bf16 v[78:81], v[184:187], v[168:171], v[78:81]
	v_mfma_f32_16x16x32_bf16 v[46:49], v[184:187], v[172:175], v[46:49]
	ds_read_b128 v[184:187], v0 offset:22528
	s_waitcnt lgkmcnt(3)
; #define BLOADG(kt) do { \
;     _Pragma("unroll") for (int i = 0; i < 2; ++i) ra[i] = *(const u32x4*)(ap + (size_t)(64 * i) * lda + (kt) * 32); \
;     _Pragma("unroll") for (int i = 0; i < 4; ++i) rb[i] = *(const u32x4*)(bp + (size_t)((i & 1) * s1 + (i >> 1) * s2) * ldb + (kt) * 32); } while (0)
; #define BSTOREG(st) do { \
;     _Pragma("unroll") for (int i = 0; i < 2; ++i) *(u32x4*)(sA + (st) * BGA + so + 64 * i * 32) = ra[i]; \
;     _Pragma("unroll") for (int i = 0; i < 4; ++i) *(u32x4*)(sB + (st) * BGB + so + 64 * i * 32) = rb[i]; } while (0)
;     ...
;   for (int kt = 0; kt < nk; ++kt) {
;     const int cur = kt & 1;
;     if (kt + 1 < nk) { BSTOREG(cur ^ 1); if (kt + 2 < nk) BLOADG(kt + 2); }
;     const bf16_t* cA = sA + cur * BGA + (wm * 64) * 32 + fo; const bf16_t* cB = sB + cur * BGB + (wn * 128) * 32 + fo;
;     bf16x8 af[4];
; #pragma unroll
;     for (int mi = 0; mi < 4; ++mi) af[mi] = *(const bf16x8*)(cA + mi * 16 * 32);
; #pragma unroll
;     for (int nh = 0; nh < 2; ++nh) {
;       bf16x8 bfr[4];
; #pragma unroll
;       for (int ni = 0; ni < 4; ++ni) bfr[ni] = *(const bf16x8*)(cB + (nh * 4 + ni) * 16 * 32);
; #pragma unroll
;       for (int mi = 0; mi < 4; ++mi)
; #pragma unroll
;         for (int ni = 0; ni < 4; ++ni) acc[mi][nh * 4 + ni] = __builtin_amdgcn_mfma_f32_16x16x32_bf16(bfr[ni], af[mi], acc[mi][nh * 4 + ni], 0, 0, 0);
;     }
;     __syncthreads();
	v_mfma_f32_16x16x32_bf16 v[114:117], v[206:209], v[160:163], v[114:117]
	v_mfma_f32_16x16x32_bf16 v[98:101], v[206:209], v[164:167], v[98:101]
	v_mfma_f32_16x16x32_bf16 v[70:73], v[206:209], v[168:171], v[70:73]
	v_mfma_f32_16x16x32_bf16 v[38:41], v[206:209], v[172:175], v[38:41]
	ds_read_b128 v[206:209], v0 offset:23552
	s_waitcnt lgkmcnt(3)
	v_mfma_f32_16x16x32_bf16 v[90:93], v[176:179], v[160:163], v[90:93]
	v_mfma_f32_16x16x32_bf16 v[58:61], v[176:179], v[164:167], v[58:61]
	v_mfma_f32_16x16x32_bf16 v[30:33], v[176:179], v[168:171], v[30:33]
	v_mfma_f32_16x16x32_bf16 v[14:17], v[176:179], v[172:175], v[14:17]
	s_waitcnt vmcnt(0)
	s_waitcnt lgkmcnt(2)
	v_mfma_f32_16x16x32_bf16 v[82:85], v[180:183], v[160:163], v[82:85]
	ds_write_b128 v227, v[126:129] offset:33792
	v_mfma_f32_16x16x32_bf16 v[50:53], v[180:183], v[164:167], v[50:53]
	ds_write_b128 v227, v[122:125] offset:37888
	v_mfma_f32_16x16x32_bf16 v[26:29], v[180:183], v[168:171], v[26:29]
	ds_write_b128 v228, v[138:141] offset:49152
	v_mfma_f32_16x16x32_bf16 v[10:13], v[180:183], v[172:175], v[10:13]
	ds_write_b128 v228, v[134:137] offset:53248
	s_waitcnt lgkmcnt(5)
	v_mfma_f32_16x16x32_bf16 v[74:77], v[184:187], v[160:163], v[74:77]
	ds_write_b128 v228, v[130:133] offset:57344
	v_mfma_f32_16x16x32_bf16 v[42:45], v[184:187], v[164:167], v[42:45]
	ds_write_b128 v227, v[142:145] offset:28672
	v_mfma_f32_16x16x32_bf16 v[22:25], v[184:187], v[168:171], v[22:25]
	v_mfma_f32_16x16x32_bf16 v[6:9], v[184:187], v[172:175], v[6:9]
	s_waitcnt lgkmcnt(0)
	s_barrier
	v_mfma_f32_16x16x32_bf16 v[66:69], v[206:209], v[160:163], v[66:69]
	v_mfma_f32_16x16x32_bf16 v[34:37], v[206:209], v[164:167], v[34:37]
	v_mfma_f32_16x16x32_bf16 v[18:21], v[206:209], v[168:171], v[18:21]
	v_mfma_f32_16x16x32_bf16 v[2:5], v[206:209], v[172:175], v[2:5]
	ds_read_b128 v[160:163], v158 offset:8192
	ds_read_b128 v[164:167], v158 offset:9216
	ds_read_b128 v[168:171], v158 offset:10240
	ds_read_b128 v[172:175], v158 offset:11264
	ds_read_b128 v[176:179], v0 offset:32768
	ds_read_b128 v[180:183], v0 offset:33792
	ds_read_b128 v[184:187], v0 offset:34816
	ds_read_b128 v[206:209], v0 offset:35840
	s_waitcnt lgkmcnt(7)
	s_waitcnt lgkmcnt(3)
	v_mfma_f32_16x16x32_bf16 v[150:153], v[176:179], v[160:163], v[150:153]
	v_mfma_f32_16x16x32_bf16 v[110:113], v[176:179], v[164:167], v[110:113]
	v_mfma_f32_16x16x32_bf16 v[94:97], v[176:179], v[168:171], v[94:97]
	v_mfma_f32_16x16x32_bf16 v[62:65], v[176:179], v[172:175], v[62:65]
	ds_read_b128 v[176:179], v0 offset:36864
	s_mov_b32 m0, s22
	s_nop 0
	global_load_lds_dwordx4 v154, s[0:1]
	global_load_dwordx4 v[126:129], v154, s[0:1] offset:64
	s_waitcnt lgkmcnt(3)
	v_mfma_f32_16x16x32_bf16 v[146:149], v[180:183], v[160:163], v[146:149]
	v_mfma_f32_16x16x32_bf16 v[106:109], v[180:183], v[164:167], v[106:109]
	v_mfma_f32_16x16x32_bf16 v[86:89], v[180:183], v[168:171], v[86:89]
	v_mfma_f32_16x16x32_bf16 v[54:57], v[180:183], v[172:175], v[54:57]
	ds_read_b128 v[180:183], v0 offset:37888
	s_add_u32 m0, s22, 0x1000
	s_nop 0
	global_load_lds_dwordx4 v155, s[0:1]
	global_load_dwordx4 v[122:125], v155, s[0:1] offset:64
	s_waitcnt lgkmcnt(3)
	v_mfma_f32_16x16x32_bf16 v[118:121], v[184:187], v[160:163], v[118:121]
	v_mfma_f32_16x16x32_bf16 v[102:105], v[184:187], v[164:167], v[102:105]
	v_mfma_f32_16x16x32_bf16 v[78:81], v[184:187], v[168:171], v[78:81]
	v_mfma_f32_16x16x32_bf16 v[46:49], v[184:187], v[172:175], v[46:49]
	ds_read_b128 v[184:187], v0 offset:38912
	s_add_u32 m0, s22, 0x4000
	s_nop 0
	global_load_lds_dwordx4 v154, s[24:25]
	global_load_dwordx4 v[138:141], v154, s[24:25] offset:64
	s_waitcnt lgkmcnt(3)
	v_mfma_f32_16x16x32_bf16 v[114:117], v[206:209], v[160:163], v[114:117]
	v_mfma_f32_16x16x32_bf16 v[98:101], v[206:209], v[164:167], v[98:101]
	v_mfma_f32_16x16x32_bf16 v[70:73], v[206:209], v[168:171], v[70:73]
	v_mfma_f32_16x16x32_bf16 v[38:41], v[206:209], v[172:175], v[38:41]
	ds_read_b128 v[206:209], v0 offset:39936
	s_add_u32 m0, s22, 0x5000
	s_nop 0
	global_load_lds_dwordx4 v155, s[24:25]
	global_load_dwordx4 v[134:137], v155, s[24:25] offset:64
	s_waitcnt lgkmcnt(3)
	v_mfma_f32_16x16x32_bf16 v[90:93], v[176:179], v[160:163], v[90:93]
	v_mfma_f32_16x16x32_bf16 v[58:61], v[176:179], v[164:167], v[58:61]
	v_mfma_f32_16x16x32_bf16 v[30:33], v[176:179], v[168:171], v[30:33]
	v_mfma_f32_16x16x32_bf16 v[14:17], v[176:179], v[172:175], v[14:17]
	s_add_u32 m0, s22, 0x6000
	s_nop 0
	global_load_lds_dwordx4 v156, s[24:25]
	global_load_dwordx4 v[130:133], v156, s[24:25] offset:64
	s_waitcnt lgkmcnt(2)
	v_mfma_f32_16x16x32_bf16 v[82:85], v[180:183], v[160:163], v[82:85]
	v_mfma_f32_16x16x32_bf16 v[50:53], v[180:183], v[164:167], v[50:53]
	v_mfma_f32_16x16x32_bf16 v[26:29], v[180:183], v[168:171], v[26:29]
	v_mfma_f32_16x16x32_bf16 v[10:13], v[180:183], v[172:175], v[10:13]
	s_add_u32 m0, s22, 0x7000
	s_nop 0
	global_load_lds_dwordx4 v157, s[24:25]
	global_load_dwordx4 v[142:145], v157, s[24:25] offset:64
	s_add_u32 s0, s0, 0x80
	s_addc_u32 s1, s1, 0
	s_add_u32 s24, s24, 0x80
	s_addc_u32 s25, s25, 0
	s_waitcnt lgkmcnt(1)
	v_mfma_f32_16x16x32_bf16 v[74:77], v[184:187], v[160:163], v[74:77]
	v_mfma_f32_16x16x32_bf16 v[42:45], v[184:187], v[164:167], v[42:45]
	v_mfma_f32_16x16x32_bf16 v[22:25], v[184:187], v[168:171], v[22:25]
	v_mfma_f32_16x16x32_bf16 v[6:9], v[184:187], v[172:175], v[6:9]
	s_waitcnt lgkmcnt(0)
	s_barrier
; #define BLOADG(kt) do { \
;     _Pragma("unroll") for (int i = 0; i < 2; ++i) ra[i] = *(const u32x4*)(ap + (size_t)(64 * i) * lda + (kt) * 32); \
;     _Pragma("unroll") for (int i = 0; i < 4; ++i) rb[i] = *(const u32x4*)(bp + (size_t)((i & 1) * s1 + (i >> 1) * s2) * ldb + (kt) * 32); } while (0)
; #define BSTOREG(st) do { \
;     _Pragma("unroll") for (int i = 0; i < 2; ++i) *(u32x4*)(sA + (st) * BGA + so + 64 * i * 32) = ra[i]; \
;     _Pragma("unroll") for (int i = 0; i < 4; ++i) *(u32x4*)(sB + (st) * BGB + so + 64 * i * 32) = rb[i]; } while (0)
;     ...
;   for (int kt = 0; kt < nk; ++kt) {
;     const int cur = kt & 1;
;     if (kt + 1 < nk) { BSTOREG(cur ^ 1); if (kt + 2 < nk) BLOADG(kt + 2); }
;     const bf16_t* cA = sA + cur * BGA + (wm * 64) * 32 + fo; const bf16_t* cB = sB + cur * BGB + (wn * 128) * 32 + fo;
;     bf16x8 af[4];
; #pragma unroll
;     for (int mi = 0; mi < 4; ++mi) af[mi] = *(const bf16x8*)(cA + mi * 16 * 32);
; #pragma unroll
;     for (int nh = 0; nh < 2; ++nh) {
;       bf16x8 bfr[4];
; #pragma unroll
;       for (int ni = 0; ni < 4; ++ni) bfr[ni] = *(const bf16x8*)(cB + (nh * 4 + ni) * 16 * 32);
; #pragma unroll
;       for (int mi = 0; mi < 4; ++mi)
; #pragma unroll
;         for (int ni = 0; ni < 4; ++ni) acc[mi][nh * 4 + ni] = __builtin_amdgcn_mfma_f32_16x16x32_bf16(bfr[ni], af[mi], acc[mi][nh * 4 + ni], 0, 0, 0);
;     }
;     __syncthreads();
	v_mfma_f32_16x16x32_bf16 v[66:69], v[206:209], v[160:163], v[66:69]
	v_mfma_f32_16x16x32_bf16 v[34:37], v[206:209], v[164:167], v[34:37]
	v_mfma_f32_16x16x32_bf16 v[18:21], v[206:209], v[168:171], v[18:21]
	v_mfma_f32_16x16x32_bf16 v[2:5], v[206:209], v[172:175], v[2:5]
	ds_read_b128 v[160:163], v226 offset:33792
	ds_read_b128 v[164:167], v226 offset:34816
	ds_read_b128 v[168:171], v226 offset:35840
	ds_read_b128 v[172:175], v226 offset:36864
	ds_read_b128 v[176:179], v0 offset:49152
	ds_read_b128 v[180:183], v0 offset:50176
	ds_read_b128 v[184:187], v0 offset:51200
	ds_read_b128 v[206:209], v0 offset:52224
	s_waitcnt lgkmcnt(7)
	s_waitcnt lgkmcnt(3)
	v_mfma_f32_16x16x32_bf16 v[150:153], v[176:179], v[160:163], v[150:153]
	v_mfma_f32_16x16x32_bf16 v[110:113], v[176:179], v[164:167], v[110:113]
	v_mfma_f32_16x16x32_bf16 v[94:97], v[176:179], v[168:171], v[94:97]
	v_mfma_f32_16x16x32_bf16 v[62:65], v[176:179], v[172:175], v[62:65]
	ds_read_b128 v[176:179], v0 offset:53248
	s_waitcnt lgkmcnt(3)
	v_mfma_f32_16x16x32_bf16 v[146:149], v[180:183], v[160:163], v[146:149]
	v_mfma_f32_16x16x32_bf16 v[106:109], v[180:183], v[164:167], v[106:109]
	v_mfma_f32_16x16x32_bf16 v[86:89], v[180:183], v[168:171], v[86:89]
	v_mfma_f32_16x16x32_bf16 v[54:57], v[180:183], v[172:175], v[54:57]
	ds_read_b128 v[180:183], v0 offset:54272
	s_waitcnt lgkmcnt(3)
	v_mfma_f32_16x16x32_bf16 v[118:121], v[184:187], v[160:163], v[118:121]
	v_mfma_f32_16x16x32_bf16 v[102:105], v[184:187], v[164:167], v[102:105]
	v_mfma_f32_16x16x32_bf16 v[78:81], v[184:187], v[168:171], v[78:81]
	v_mfma_f32_16x16x32_bf16 v[46:49], v[184:187], v[172:175], v[46:49]
	ds_read_b128 v[184:187], v0 offset:55296
	s_waitcnt lgkmcnt(3)
	v_mfma_f32_16x16x32_bf16 v[114:117], v[206:209], v[160:163], v[114:117]
	v_mfma_f32_16x16x32_bf16 v[98:101], v[206:209], v[164:167], v[98:101]
	v_mfma_f32_16x16x32_bf16 v[70:73], v[206:209], v[168:171], v[70:73]
	v_mfma_f32_16x16x32_bf16 v[38:41], v[206:209], v[172:175], v[38:41]
	ds_read_b128 v[206:209], v0 offset:56320
	s_waitcnt lgkmcnt(3)
	v_mfma_f32_16x16x32_bf16 v[90:93], v[176:179], v[160:163], v[90:93]
	v_mfma_f32_16x16x32_bf16 v[58:61], v[176:179], v[164:167], v[58:61]
	v_mfma_f32_16x16x32_bf16 v[30:33], v[176:179], v[168:171], v[30:33]
	v_mfma_f32_16x16x32_bf16 v[14:17], v[176:179], v[172:175], v[14:17]
	s_waitcnt vmcnt(0)
	s_waitcnt lgkmcnt(2)
	v_mfma_f32_16x16x32_bf16 v[82:85], v[180:183], v[160:163], v[82:85]
	ds_write_b128 v228, v[126:129] offset:8192
	v_mfma_f32_16x16x32_bf16 v[50:53], v[180:183], v[164:167], v[50:53]
	ds_write_b128 v228, v[122:125] offset:12288
	v_mfma_f32_16x16x32_bf16 v[26:29], v[180:183], v[168:171], v[26:29]
	ds_write_b128 v228, v[138:141] offset:32768
	v_mfma_f32_16x16x32_bf16 v[10:13], v[180:183], v[172:175], v[10:13]
	ds_write_b128 v228, v[134:137] offset:36864
	s_waitcnt lgkmcnt(5)
	v_mfma_f32_16x16x32_bf16 v[74:77], v[184:187], v[160:163], v[74:77]
	ds_write_b128 v228, v[130:133] offset:40960
	v_mfma_f32_16x16x32_bf16 v[42:45], v[184:187], v[164:167], v[42:45]
	ds_write_b128 v228, v[142:145] offset:45056
	v_mfma_f32_16x16x32_bf16 v[22:25], v[184:187], v[168:171], v[22:25]
	v_mfma_f32_16x16x32_bf16 v[6:9], v[184:187], v[172:175], v[6:9]
	s_waitcnt lgkmcnt(0)
	s_barrier
	v_mfma_f32_16x16x32_bf16 v[66:69], v[206:209], v[160:163], v[66:69]
	v_mfma_f32_16x16x32_bf16 v[34:37], v[206:209], v[164:167], v[34:37]
	v_mfma_f32_16x16x32_bf16 v[18:21], v[206:209], v[168:171], v[18:21]
	v_mfma_f32_16x16x32_bf16 v[2:5], v[206:209], v[172:175], v[2:5]
	s_add_i32 s13, s13, 1
	s_cmp_lg_u32 s13, 5
	s_cbranch_scc1 .LBB0_249
	ds_read_b128 v[122:125], v158
	ds_read_b128 v[126:129], v158 offset:1024
	ds_read_b128 v[130:133], v158 offset:2048
	ds_read_b128 v[134:137], v158 offset:3072
	ds_read_b128 v[138:141], v0 offset:16384
	ds_read_b128 v[142:145], v0 offset:17408
	ds_read_b128 v[154:157], v0 offset:18432
	ds_read_b128 v[160:163], v0 offset:19456
	v_readlane_b32 s0, v255, 3
	s_waitcnt lgkmcnt(3)
	v_mfma_f32_16x16x32_bf16 v[150:153], v[138:141], v[122:125], v[150:153]
	v_readlane_b32 s1, v255, 4
	v_mfma_f32_16x16x32_bf16 v[110:113], v[138:141], v[126:129], v[110:113]
	s_waitcnt lgkmcnt(0)
	v_mfma_f32_16x16x32_bf16 v[168:171], v[160:163], v[126:129], v[98:101]
	v_mfma_f32_16x16x32_bf16 v[94:97], v[138:141], v[130:133], v[94:97]
	v_mfma_f32_16x16x32_bf16 v[172:175], v[142:145], v[130:133], v[86:89]
	v_mfma_f32_16x16x32_bf16 v[176:179], v[160:163], v[130:133], v[70:73]
	v_mfma_f32_16x16x32_bf16 v[62:65], v[138:141], v[134:137], v[62:65]
	v_mfma_f32_16x16x32_bf16 v[138:141], v[160:163], v[134:137], v[38:41]
	s_nop 2
	ds_read_b128 v[38:41], v0 offset:20480
	ds_read_b128 v[70:73], v0 offset:21504
	ds_read_b128 v[86:89], v0 offset:22528
	ds_read_b128 v[98:101], v0 offset:23552
	s_waitcnt vmcnt(0)
	s_waitcnt lgkmcnt(0)
	s_barrier
; DI unsigned pack2(float a, float b) { f2_t v = {a, b}; bf2_t r = __builtin_convertvector(v, bf2_t); return __builtin_bit_cast(unsigned, r); }
;     ...
;     const bf16_t* cA = sA + cur * BGA + (wm * 64) * 32 + fo; const bf16_t* cB = sB + cur * BGB + (wn * 128) * 32 + fo;
;     bf16x8 af[4];
; #pragma unroll
;     for (int mi = 0; mi < 4; ++mi) af[mi] = *(const bf16x8*)(cA + mi * 16 * 32);
; #pragma unroll
;     for (int nh = 0; nh < 2; ++nh) {
;       bf16x8 bfr[4];
; #pragma unroll
;       for (int ni = 0; ni < 4; ++ni) bfr[ni] = *(const bf16x8*)(cB + (nh * 4 + ni) * 16 * 32);
; #pragma unroll
;       for (int mi = 0; mi < 4; ++mi)
; #pragma unroll
;         for (int ni = 0; ni < 4; ++ni) acc[mi][nh * 4 + ni] = __builtin_amdgcn_mfma_f32_16x16x32_bf16(bfr[ni], af[mi], acc[mi][nh * 4 + ni], 0, 0, 0);
;     }
; DI void inproj_tile(const Params& p, int l, int tile, char* smem) {
;     ...
; #pragma unroll
;   for (int mi = 0; mi < 4; ++mi)
; #pragma unroll
;     for (int np = 0; np < 4; ++np) {
;       size_t row = (size_t)mt * 128 + wm * 64 + mi * 16 + fr; int col = nt * 256 + wn * 128 + (2 * np + (fq & 1)) * 16 + (fq >> 1) * 8;
;       uint2 a, b;
;       a.x = pack2(acc[mi][2 * np][0], acc[mi][2 * np][1]); a.y = pack2(acc[mi][2 * np][2], acc[mi][2 * np][3]);
;       b.x = pack2(acc[mi][2 * np + 1][0], acc[mi][2 * np + 1][1]); b.y = pack2(acc[mi][2 * np + 1][2], acc[mi][2 * np + 1][3]);
;       *(uint4*)(P_PROJ + row * PW + col) = widen16(a, b);
;     }
	v_mfma_f32_16x16x32_bf16 v[78:81], v[154:157], v[130:133], v[78:81]
	v_mfma_f32_16x16x32_bf16 v[54:57], v[142:145], v[134:137], v[54:57]
	v_mfma_f32_16x16x32_bf16 v[46:49], v[154:157], v[134:137], v[46:49]
	v_mfma_f32_16x16x32_bf16 v[30:33], v[38:41], v[130:133], v[30:33]
	v_mfma_f32_16x16x32_bf16 v[26:29], v[70:73], v[130:133], v[26:29]
	v_mfma_f32_16x16x32_bf16 v[22:25], v[86:89], v[130:133], v[22:25]
	v_mfma_f32_16x16x32_bf16 v[18:21], v[98:101], v[130:133], v[18:21]
	v_mfma_f32_16x16x32_bf16 v[130:133], v[38:41], v[134:137], v[14:17]
	v_mfma_f32_16x16x32_bf16 v[180:183], v[70:73], v[134:137], v[10:13]
	v_mfma_f32_16x16x32_bf16 v[184:187], v[86:89], v[134:137], v[6:9]
	v_mfma_f32_16x16x32_bf16 v[134:137], v[98:101], v[134:137], v[2:5]
	ds_read_b128 v[206:209], v158 offset:8192
	ds_read_b128 v[210:213], v158 offset:9216
	ds_read_b128 v[214:217], v158 offset:10240
	ds_read_b128 v[218:221], v158 offset:11264
	ds_read_b128 v[2:5], v0 offset:32768
	ds_read_b128 v[6:9], v0 offset:33792
	ds_read_b128 v[222:225], v0 offset:34816
	ds_read_b128 v[226:229], v0 offset:35840
	v_mfma_f32_16x16x32_bf16 v[118:121], v[154:157], v[122:125], v[118:121]
	v_mfma_f32_16x16x32_bf16 v[114:117], v[160:163], v[122:125], v[114:117]
	v_mfma_f32_16x16x32_bf16 v[106:109], v[142:145], v[126:129], v[106:109]
	v_mfma_f32_16x16x32_bf16 v[90:93], v[38:41], v[122:125], v[90:93]
	v_mfma_f32_16x16x32_bf16 v[58:61], v[38:41], v[126:129], v[58:61]
	v_mfma_f32_16x16x32_bf16 v[146:149], v[142:145], v[122:125], v[146:149]
	v_mfma_f32_16x16x32_bf16 v[164:167], v[154:157], v[126:129], v[102:105]
	v_mfma_f32_16x16x32_bf16 v[142:145], v[70:73], v[122:125], v[82:85]
	v_mfma_f32_16x16x32_bf16 v[74:77], v[86:89], v[122:125], v[74:77]
	v_mfma_f32_16x16x32_bf16 v[122:125], v[98:101], v[122:125], v[66:69]
	v_mfma_f32_16x16x32_bf16 v[154:157], v[70:73], v[126:129], v[50:53]
	v_mfma_f32_16x16x32_bf16 v[160:163], v[86:89], v[126:129], v[42:45]
	v_mfma_f32_16x16x32_bf16 v[126:129], v[98:101], v[126:129], v[34:37]
	s_waitcnt lgkmcnt(1)
	v_mfma_f32_16x16x32_bf16 v[102:105], v[222:225], v[206:209], v[118:121]
	s_waitcnt lgkmcnt(0)
	v_mfma_f32_16x16x32_bf16 v[98:101], v[226:229], v[206:209], v[114:117]
	v_mfma_f32_16x16x32_bf16 v[86:89], v[2:5], v[210:213], v[110:113]
	s_nop 4
	v_cvt_pk_bf16_f32 v102, v102, v103
	v_cvt_pk_bf16_f32 v103, v104, v105
	v_cvt_pk_bf16_f32 v104, v98, v99
	v_mfma_f32_16x16x32_bf16 v[82:85], v[6:9], v[210:213], v[106:109]
	s_nop 2
	ds_read_b128 v[106:109], v0 offset:36864
	ds_read_b128 v[110:113], v0 offset:37888
	ds_read_b128 v[114:117], v0 offset:38912
	ds_read_b128 v[118:121], v0 offset:39936
	s_waitcnt lgkmcnt(0)
	s_barrier
	v_mfma_f32_16x16x32_bf16 v[150:153], v[2:5], v[206:209], v[150:153]
	v_mov_b32 v0, v188
	v_cvt_pk_bf16_f32 v105, v100, v101
	v_mfma_f32_16x16x32_bf16 v[50:53], v[2:5], v[214:217], v[94:97]
	v_cvt_pk_bf16_f32 v86, v86, v87
	v_cvt_pk_bf16_f32 v87, v88, v89
	v_cvt_pk_bf16_f32 v88, v82, v83
	v_mfma_f32_16x16x32_bf16 v[14:17], v[2:5], v[218:221], v[62:65]
	v_cvt_pk_bf16_f32 v89, v84, v85
	v_permlane16_swap_b32_e32 v102, v104
	v_mfma_f32_16x16x32_bf16 v[2:5], v[226:229], v[218:221], v[138:141]
	v_permlane16_swap_b32_e32 v103, v105
	v_permlane16_swap_b32_e32 v86, v88
	v_mfma_f32_16x16x32_bf16 v[138:141], v[106:109], v[206:209], v[90:93]
	v_permlane16_swap_b32_e32 v87, v89
	v_cvt_pk_bf16_f32 v50, v50, v51
	v_mfma_f32_16x16x32_bf16 v[94:97], v[106:109], v[210:213], v[58:61]
	v_cvt_pk_bf16_f32 v51, v52, v53
	v_cvt_pk_bf16_f32 v14, v14, v15
	v_cvt_pk_bf16_f32 v15, v16, v17
	v_mfma_f32_16x16x32_bf16 v[62:65], v[106:109], v[214:217], v[30:33]
	s_nop 0
	v_cvt_pk_bf16_f32 v98, v138, v139
	v_cvt_pk_bf16_f32 v99, v140, v141
	v_mfma_f32_16x16x32_bf16 v[30:33], v[106:109], v[218:221], v[130:133]
	v_mov_b32 v106, v188
	v_and_b32_e32 v107, 15, v0
	v_lshrrev_b32_e32 v108, 1, v106
	v_and_b32_e32 v108, 64, v108
	v_or3_b32 v107, v107, v108, s12
	v_lshrrev_b32_e32 v108, 2, v0
	v_mfma_f32_16x16x32_bf16 v[146:149], v[6:9], v[206:209], v[146:149]
	v_lshlrev_b32_e32 v106, 1, v106
	v_and_b32_e32 v108, 8, v108
	v_and_b32_e32 v106, 0x80, v106
	v_and_or_b32 v0, v0, 16, v108
	v_mfma_f32_16x16x32_bf16 v[70:73], v[222:225], v[210:213], v[164:167]
	v_mfma_f32_16x16x32_bf16 v[38:41], v[222:225], v[214:217], v[78:81]
	v_mfma_f32_16x16x32_bf16 v[10:13], v[6:9], v[218:221], v[54:57]
	s_nop 5
	v_cvt_pk_bf16_f32 v70, v70, v71
	v_cvt_pk_bf16_f32 v71, v72, v73
	v_cvt_pk_bf16_f32 v38, v38, v39
	v_mfma_f32_16x16x32_bf16 v[164:167], v[114:117], v[206:209], v[74:77]
	v_cvt_pk_bf16_f32 v39, v40, v41
	v_cvt_pk_bf16_f32 v16, v10, v11
	v_cvt_pk_bf16_f32 v17, v12, v13
	v_mfma_f32_16x16x32_bf16 v[78:81], v[114:117], v[210:213], v[160:163]
	v_permlane16_swap_b32_e32 v14, v16
	v_permlane16_swap_b32_e32 v15, v17
	v_mfma_f32_16x16x32_bf16 v[54:57], v[114:117], v[214:217], v[22:25]
	v_mfma_f32_16x16x32_bf16 v[22:25], v[114:117], v[218:221], v[184:187]
	v_or3_b32 v114, v0, v106, s11
	v_mul_u32_u24_e32 v0, 0x1300, v107
	v_lshlrev_b32_e32 v0, 1, v0
	v_mfma_f32_16x16x32_bf16 v[42:45], v[6:9], v[214:217], v[172:175]
	v_ashrrev_i32_e32 v115, 31, v114
	v_lshl_add_u64 v[106:107], s[0:1], 0, v[0:1]
	v_lshlrev_b64 v[108:109], 1, v[114:115]
	v_mfma_f32_16x16x32_bf16 v[66:69], v[226:229], v[210:213], v[168:171]
; DI unsigned pack2(float a, float b) { f2_t v = {a, b}; bf2_t r = __builtin_convertvector(v, bf2_t); return __builtin_bit_cast(unsigned, r); }
; DI void inproj_tile(const Params& p, int l, int tile, char* smem) {
;     ...
; #pragma unroll
;   for (int mi = 0; mi < 4; ++mi)
; #pragma unroll
;     for (int np = 0; np < 4; ++np) {
;       size_t row = (size_t)mt * 128 + wm * 64 + mi * 16 + fr; int col = nt * 256 + wn * 128 + (2 * np + (fq & 1)) * 16 + (fq >> 1) * 8;
;       uint2 a, b;
;       a.x = pack2(acc[mi][2 * np][0], acc[mi][2 * np][1]); a.y = pack2(acc[mi][2 * np][2], acc[mi][2 * np][3]);
;       b.x = pack2(acc[mi][2 * np + 1][0], acc[mi][2 * np + 1][1]); b.y = pack2(acc[mi][2 * np + 1][2], acc[mi][2 * np + 1][3]);
;       *(uint4*)(P_PROJ + row * PW + col) = widen16(a, b);
;     }
; DI void run_phase(const Params& p, int ph, char* smem, bool never) {
;     ...
;       for (int w = lb; w < 64 * 8 + 96; w += nl) {
;         const int it = w >> 6, l64 = w & 63;
;         int mt, nt;
;         if (it < 8) { const int a = it >> 1, gn = it & 1; mt = 8 * (xcd + 8 * a) + (l64 & 7); nt = 8 * gn + (l64 >> 3); }
;         else { const int q = (it - 8) * 64 + l64; const int ml = q / 3; mt = 8 * (xcd + 8 * (ml >> 3)) + (ml & 7); nt = 16 + q % 3; }
;         inproj_tile(p, l, nt * 256 + mt, smem);
	v_lshl_add_u64 v[116:117], v[106:107], 0, v[108:109]
	s_mov_b64 s[0:1], 0x26000
	v_lshl_add_u64 v[82:83], v[106:107], 0, s[0:1]
	v_mfma_f32_16x16x32_bf16 v[34:37], v[226:229], v[214:217], v[176:179]
	s_mov_b64 s[0:1], 0x4c000
	v_lshl_add_u64 v[84:85], v[82:83], 0, v[108:109]
	v_cvt_pk_bf16_f32 v52, v42, v43
	v_mfma_f32_16x16x32_bf16 v[6:9], v[222:225], v[218:221], v[46:49]
	v_lshl_add_u64 v[42:43], v[106:107], 0, s[0:1]
	s_mov_b64 s[0:1], 0x72000
	global_store_dwordx4 v[116:117], v[102:105], off offset:64
	v_mfma_f32_16x16x32_bf16 v[142:145], v[110:113], v[206:209], v[142:145]
	global_store_dwordx4 v[84:85], v[86:89], off
	v_or_b32_e32 v102, 64, v114
	v_cvt_pk_bf16_f32 v72, v66, v67
	v_mfma_f32_16x16x32_bf16 v[90:93], v[110:113], v[210:213], v[154:157]
	v_cvt_pk_bf16_f32 v73, v68, v69
	v_cvt_pk_bf16_f32 v40, v34, v35
	v_cvt_pk_bf16_f32 v41, v36, v37
	v_mfma_f32_16x16x32_bf16 v[58:61], v[110:113], v[214:217], v[26:29]
	v_lshl_add_u64 v[10:11], v[106:107], 0, s[0:1]
	v_cvt_pk_bf16_f32 v6, v6, v7
	v_cvt_pk_bf16_f32 v7, v8, v9
	v_mfma_f32_16x16x32_bf16 v[26:29], v[110:113], v[218:221], v[180:183]
	v_cvt_pk_bf16_f32 v110, v150, v151
	v_cvt_pk_bf16_f32 v111, v152, v153
	v_cvt_pk_bf16_f32 v112, v146, v147
	v_cvt_pk_bf16_f32 v113, v148, v149
	s_nop 0
	v_permlane16_swap_b32_e32 v110, v112
	v_permlane16_swap_b32_e32 v111, v113
	global_store_dwordx4 v[116:117], v[110:113], off
	v_mfma_f32_16x16x32_bf16 v[122:125], v[118:121], v[206:209], v[122:125]
	v_cvt_pk_bf16_f32 v8, v2, v3
	v_or_b32_e32 v110, 32, v114
	v_ashrrev_i32_e32 v111, 31, v110
	v_mfma_f32_16x16x32_bf16 v[74:77], v[118:121], v[210:213], v[126:129]
	v_lshlrev_b64 v[84:85], 1, v[110:111]
	v_cvt_pk_bf16_f32 v9, v4, v5
	v_ashrrev_i32_e32 v103, 31, v102
	v_mfma_f32_16x16x32_bf16 v[46:49], v[118:121], v[214:217], v[18:21]
	v_permlane16_swap_b32_e32 v70, v72
	v_permlane16_swap_b32_e32 v71, v73
	v_mfma_f32_16x16x32_bf16 v[18:21], v[118:121], v[218:221], v[134:137]
	v_lshl_add_u64 v[66:67], v[82:83], 0, v[84:85]
	v_permlane16_swap_b32_e32 v38, v40
	v_permlane16_swap_b32_e32 v39, v41
	v_lshl_add_u64 v[34:35], v[42:43], 0, v[84:85]
	v_permlane16_swap_b32_e32 v6, v8
	v_permlane16_swap_b32_e32 v7, v9
	v_lshl_add_u64 v[2:3], v[10:11], 0, v[84:85]
	v_cvt_pk_bf16_f32 v100, v142, v143
	v_cvt_pk_bf16_f32 v101, v144, v145
	v_or_b32_e32 v104, 0x60, v114
	global_store_dwordx4 v[66:67], v[70:73], off
	v_cvt_pk_bf16_f32 v66, v94, v95
	v_cvt_pk_bf16_f32 v67, v96, v97
	v_cvt_pk_bf16_f32 v68, v90, v91
	v_cvt_pk_bf16_f32 v69, v92, v93
	v_lshlrev_b64 v[70:71], 1, v[102:103]
	global_store_dwordx4 v[34:35], v[38:41], off
	v_cvt_pk_bf16_f32 v34, v62, v63
	v_cvt_pk_bf16_f32 v35, v64, v65
	v_cvt_pk_bf16_f32 v36, v58, v59
	v_cvt_pk_bf16_f32 v37, v60, v61
	global_store_dwordx4 v[2:3], v[6:9], off
	v_cvt_pk_bf16_f32 v2, v30, v31
	v_cvt_pk_bf16_f32 v3, v32, v33
	v_cvt_pk_bf16_f32 v4, v26, v27
	v_cvt_pk_bf16_f32 v5, v28, v29
	v_permlane16_swap_b32_e32 v98, v100
	v_permlane16_swap_b32_e32 v99, v101
	v_ashrrev_i32_e32 v105, 31, v104
	v_permlane16_swap_b32_e32 v66, v68
	v_permlane16_swap_b32_e32 v67, v69
	v_lshl_add_u64 v[72:73], v[82:83], 0, v[70:71]
	v_permlane16_swap_b32_e32 v34, v36
	v_permlane16_swap_b32_e32 v35, v37
	v_lshl_add_u64 v[38:39], v[42:43], 0, v[70:71]
	v_permlane16_swap_b32_e32 v2, v4
	v_permlane16_swap_b32_e32 v3, v5
	v_lshl_add_u64 v[6:7], v[10:11], 0, v[70:71]
	v_readlane_b32 s0, v255, 33
	global_store_dwordx4 v[116:117], v[98:101], off offset:128
	global_store_dwordx4 v[72:73], v[66:69], off
	v_lshlrev_b64 v[72:73], 1, v[104:105]
	v_cvt_pk_bf16_f32 v98, v164, v165
	v_cvt_pk_bf16_f32 v99, v166, v167
	v_cvt_pk_bf16_f32 v100, v122, v123
	v_cvt_pk_bf16_f32 v101, v124, v125
	v_cvt_pk_bf16_f32 v66, v78, v79
	v_cvt_pk_bf16_f32 v67, v80, v81
	v_cvt_pk_bf16_f32 v68, v74, v75
	v_cvt_pk_bf16_f32 v69, v76, v77
	v_cvt_pk_bf16_f32 v53, v44, v45
	global_store_dwordx4 v[38:39], v[34:37], off
	global_store_dwordx4 v[6:7], v[2:5], off
	s_add_i32 s7, s7, s0
	v_cvt_pk_bf16_f32 v34, v54, v55
	v_cvt_pk_bf16_f32 v35, v56, v57
	v_cvt_pk_bf16_f32 v36, v46, v47
	v_cvt_pk_bf16_f32 v37, v48, v49
	v_cvt_pk_bf16_f32 v2, v22, v23
	v_cvt_pk_bf16_f32 v3, v24, v25
	v_cvt_pk_bf16_f32 v4, v18, v19
	v_cvt_pk_bf16_f32 v5, v20, v21
	v_permlane16_swap_b32_e32 v98, v100
	v_permlane16_swap_b32_e32 v99, v101
	v_permlane16_swap_b32_e32 v66, v68
	v_permlane16_swap_b32_e32 v67, v69
	v_lshl_add_u64 v[74:75], v[82:83], 0, v[72:73]
	v_permlane16_swap_b32_e32 v50, v52
	v_permlane16_swap_b32_e32 v51, v53
	v_lshl_add_u64 v[44:45], v[42:43], 0, v[108:109]
	v_permlane16_swap_b32_e32 v34, v36
	v_permlane16_swap_b32_e32 v35, v37
	v_lshl_add_u64 v[38:39], v[42:43], 0, v[72:73]
	v_lshl_add_u64 v[12:13], v[10:11], 0, v[108:109]
	v_permlane16_swap_b32_e32 v2, v4
	v_permlane16_swap_b32_e32 v3, v5
	v_lshl_add_u64 v[6:7], v[10:11], 0, v[72:73]
	s_cmpk_gt_i32 s7, 0x25f
	global_store_dwordx4 v[116:117], v[98:101], off offset:192
	global_store_dwordx4 v[74:75], v[66:69], off
	global_store_dwordx4 v[44:45], v[50:53], off
	global_store_dwordx4 v[38:39], v[34:37], off
	global_store_dwordx4 v[12:13], v[14:17], off
	global_store_dwordx4 v[6:7], v[2:5], off
	s_cbranch_scc0 .LBB0_244
	s_movk_i32 s11, 0x2000

; __global__ void __launch_bounds__(256, 2) mega(Params p, int ph_lo, int ph_hi) {
;   __shared__ __attribute__((aligned(16))) char smem[66048];
	.amdhsa_kernel _Z4mega6Paramsii
		.amdhsa_group_segment_fixed_size 74752
		.amdhsa_private_segment_fixed_size 0
		.amdhsa_kernarg_size 392
		.amdhsa_user_sgpr_count 2
		.amdhsa_user_sgpr_dispatch_ptr 0
		.amdhsa_user_sgpr_queue_ptr 0
		.amdhsa_user_sgpr_kernarg_segment_ptr 1
		.amdhsa_user_sgpr_dispatch_id 0
		.amdhsa_user_sgpr_kernarg_preload_length 0
		.amdhsa_user_sgpr_kernarg_preload_offset 0
		.amdhsa_user_sgpr_private_segment_size 0
		.amdhsa_uses_dynamic_stack 0
		.amdhsa_enable_private_segment 0
		.amdhsa_system_sgpr_workgroup_id_x 1
		.amdhsa_system_sgpr_workgroup_id_y 0
		.amdhsa_system_sgpr_workgroup_id_z 0
		.amdhsa_system_sgpr_workgroup_info 0
		.amdhsa_system_vgpr_workitem_id 2
		.amdhsa_next_free_vgpr 256
		.amdhsa_next_free_sgpr 100
		.amdhsa_accum_offset 256
		.amdhsa_reserve_vcc 1
		.amdhsa_float_round_mode_32 0
		.amdhsa_float_round_mode_16_64 0
		.amdhsa_float_denorm_mode_32 3
		.amdhsa_float_denorm_mode_16_64 3
		.amdhsa_dx10_clamp 1
		.amdhsa_ieee_mode 1
		.amdhsa_fp16_overflow 0
		.amdhsa_tg_split 0
		.amdhsa_exception_fp_ieee_invalid_op 0
		.amdhsa_exception_fp_denorm_src 0
		.amdhsa_exception_fp_ieee_div_zero 0
		.amdhsa_exception_fp_ieee_overflow 0
		.amdhsa_exception_fp_ieee_underflow 0
		.amdhsa_exception_fp_ieee_inexact 0
		.amdhsa_exception_int_div_zero 0
	.end_amdhsa_kernel

; __global__ void __launch_bounds__(256, 2) mega(Params p, int ph_lo, int ph_hi) {
;   __shared__ __attribute__((aligned(16))) char smem[66048];
amdhsa.kernels:
  - .agpr_count:     0
    .args:
      - .offset:         0
        .size:           128
        .value_kind:     by_value
      - .offset:         128
        .size:           4
        .value_kind:     by_value
      - .offset:         132
        .size:           4
        .value_kind:     by_value
      - .offset:         136
        .size:           4
        .value_kind:     hidden_block_count_x
      - .offset:         140
        .size:           4
        .value_kind:     hidden_block_count_y
      - .offset:         144
        .size:           4
        .value_kind:     hidden_block_count_z
      - .offset:         148
        .size:           2
        .value_kind:     hidden_group_size_x
      - .offset:         150
        .size:           2
        .value_kind:     hidden_group_size_y
      - .offset:         152
        .size:           2
        .value_kind:     hidden_group_size_z
      - .offset:         154
        .size:           2
        .value_kind:     hidden_remainder_x
      - .offset:         156
        .size:           2
        .value_kind:     hidden_remainder_y
      - .offset:         158
        .size:           2
        .value_kind:     hidden_remainder_z
      - .offset:         176
        .size:           8
        .value_kind:     hidden_global_offset_x
      - .offset:         184
        .size:           8
        .value_kind:     hidden_global_offset_y
      - .offset:         192
        .size:           8
        .value_kind:     hidden_global_offset_z
      - .offset:         200
        .size:           2
        .value_kind:     hidden_grid_dims
      - .offset:         224
        .size:           8
        .value_kind:     hidden_multigrid_sync_arg
    .group_segment_fixed_size: 74752
    .kernarg_segment_align: 8
    .kernarg_segment_size: 392
    .language:       OpenCL C
    .language_version:
      - 2
      - 0
    .max_flat_workgroup_size: 256
    .name:           _Z4mega6Paramsii
    .private_segment_fixed_size: 0
    .sgpr_count:     106
    .sgpr_spill_count: 181
    .symbol:         _Z4mega6Paramsii.kd
    .uniform_work_group_size: 1
    .uses_dynamic_stack: false
    .vgpr_count:     256
    .vgpr_spill_count: 0
    .wavefront_size: 64
